# RG-LRU tile passes: x rows of the next tile loaded one job ahead (job-end wait kept)
# speedup vs baseline: 1.0069x; 1.0069x over previous
; __device__ __forceinline__ u16 f2bf(float x) { return (u16)(cvtpk(x, 0.f) & 0xffffu); }
; __device__ __forceinline__ float fexp(float x) { return __builtin_amdgcn_exp2f(x * 1.4426950408889634f); }
; template <int PASS>
; __device__ __forceinline__ void lru_tile_phase(const Params& p, int jl, int Mrows, char* smem, int tid, int bid) {
;     ...
;     if (PASS == 2) {
;       __syncthreads();
;       const int ch = tid & 127, tg = tid >> 7;
;       const int col = n * 128 + ch;
;       float hsv[16];
; #pragma unroll
;       for (int i = 0; i < 16; ++i) { const int t = tg * 16 + i; hsv[i] = uL[(0 * 64 + t) * 128 + ch] + uL[(1 * 64 + t) * 128 + ch]; }
; #pragma unroll
;       for (int i = 0; i < 16; ++i) {
;         const int t = tg * 16 + i;
;         const float hs = hsv[i];
;         const float gt = __uint_as_float(gv[i] << 16);
;         const float z2 = 1.5957691216057308f * (gt + 0.044715f * gt * gt * gt);
;         const float gl = gt * __builtin_amdgcn_rcpf(1.f + fexp(-z2));
;         H[(size_t)(rowbase + t) * 1024 + col] = f2bf(hs * gl);
;       }
;     }
;     __syncthreads();
.Llru2_gwd:
	s_barrier
	ds_read_b128 v[0:3], v189 offset:0
	ds_read_b128 v[4:7], v189 offset:16
	ds_read_b128 v[8:11], v189 offset:32
	ds_read_b128 v[12:15], v189 offset:48
	ds_read_b128 v[16:19], v189 offset:32768
	ds_read_b128 v[20:23], v189 offset:32784
	ds_read_b128 v[24:27], v189 offset:32800
	ds_read_b128 v[28:31], v189 offset:32816
	s_lshl_b32 s0, s9, 11
	s_lshl_b32 s1, s7, 8
	s_add_u32 s0, s0, s1
	s_add_u32 s0, s28, s0
	s_addc_u32 s1, s29, 0
	s_waitcnt lgkmcnt(0)
	v_add_f32_e32 v0, v0, v16
	v_lshlrev_b32_e32 v80, 16, v92
	v_mul_f32_e32 v81, 0x3d372713, v80
	v_mul_f32_e32 v81, v81, v80
	v_fma_f32 v81, v81, v80, v80
	v_mul_f32_e32 v81, 0x3fcc422a, v81
	v_mul_f32_e32 v81, 0xbfb8aa3b, v81
	v_exp_f32_e32 v81, v81
	s_nop 0
	v_add_f32_e32 v81, 1.0, v81
	v_rcp_f32_e32 v81, v81
	s_nop 0
	v_mul_f32_e32 v81, v80, v81
	v_mul_f32_e32 v0, v0, v81
	v_add_f32_e32 v1, v1, v17
	v_and_b32_e32 v80, 0xffff0000, v92
	v_mul_f32_e32 v81, 0x3d372713, v80
	v_mul_f32_e32 v81, v81, v80
	v_fma_f32 v81, v81, v80, v80
	v_mul_f32_e32 v81, 0x3fcc422a, v81
	v_mul_f32_e32 v81, 0xbfb8aa3b, v81
	v_exp_f32_e32 v81, v81
	s_nop 0
	v_add_f32_e32 v81, 1.0, v81
	v_rcp_f32_e32 v81, v81
	s_nop 0
	v_mul_f32_e32 v81, v80, v81
	v_mul_f32_e32 v1, v1, v81
	v_add_f32_e32 v2, v2, v18
	v_lshlrev_b32_e32 v80, 16, v93
	v_mul_f32_e32 v81, 0x3d372713, v80
	v_mul_f32_e32 v81, v81, v80
	v_fma_f32 v81, v81, v80, v80
	v_mul_f32_e32 v81, 0x3fcc422a, v81
	v_mul_f32_e32 v81, 0xbfb8aa3b, v81
	v_exp_f32_e32 v81, v81
	s_nop 0
	v_add_f32_e32 v81, 1.0, v81
	v_rcp_f32_e32 v81, v81
	s_nop 0
	v_mul_f32_e32 v81, v80, v81
	v_mul_f32_e32 v2, v2, v81
	v_add_f32_e32 v3, v3, v19
	v_and_b32_e32 v80, 0xffff0000, v93
	v_mul_f32_e32 v81, 0x3d372713, v80
	v_mul_f32_e32 v81, v81, v80
	v_fma_f32 v81, v81, v80, v80
	v_mul_f32_e32 v81, 0x3fcc422a, v81
	v_mul_f32_e32 v81, 0xbfb8aa3b, v81
	v_exp_f32_e32 v81, v81
	s_nop 0
	v_add_f32_e32 v81, 1.0, v81
	v_rcp_f32_e32 v81, v81
	s_nop 0
	v_mul_f32_e32 v81, v80, v81
	v_mul_f32_e32 v3, v3, v81
	v_add_f32_e32 v4, v4, v20
	v_lshlrev_b32_e32 v80, 16, v94
	v_mul_f32_e32 v81, 0x3d372713, v80
	v_mul_f32_e32 v81, v81, v80
	v_fma_f32 v81, v81, v80, v80
	v_mul_f32_e32 v81, 0x3fcc422a, v81
	v_mul_f32_e32 v81, 0xbfb8aa3b, v81
	v_exp_f32_e32 v81, v81
	s_nop 0
	v_add_f32_e32 v81, 1.0, v81
	v_rcp_f32_e32 v81, v81
	s_nop 0
	v_mul_f32_e32 v81, v80, v81
	v_mul_f32_e32 v4, v4, v81
	v_add_f32_e32 v5, v5, v21
	v_and_b32_e32 v80, 0xffff0000, v94
	v_mul_f32_e32 v81, 0x3d372713, v80
	v_mul_f32_e32 v81, v81, v80
	v_fma_f32 v81, v81, v80, v80
	v_mul_f32_e32 v81, 0x3fcc422a, v81
	v_mul_f32_e32 v81, 0xbfb8aa3b, v81
	v_exp_f32_e32 v81, v81
	s_nop 0
	v_add_f32_e32 v81, 1.0, v81
	v_rcp_f32_e32 v81, v81
	s_nop 0
	v_mul_f32_e32 v81, v80, v81
	v_mul_f32_e32 v5, v5, v81
	v_add_f32_e32 v6, v6, v22
	v_lshlrev_b32_e32 v80, 16, v95
	v_mul_f32_e32 v81, 0x3d372713, v80
	v_mul_f32_e32 v81, v81, v80
	v_fma_f32 v81, v81, v80, v80
	v_mul_f32_e32 v81, 0x3fcc422a, v81
	v_mul_f32_e32 v81, 0xbfb8aa3b, v81
	v_exp_f32_e32 v81, v81
	s_nop 0
	v_add_f32_e32 v81, 1.0, v81
	v_rcp_f32_e32 v81, v81
	s_nop 0
	v_mul_f32_e32 v81, v80, v81
	v_mul_f32_e32 v6, v6, v81
	v_add_f32_e32 v7, v7, v23
	v_and_b32_e32 v80, 0xffff0000, v95
	v_mul_f32_e32 v81, 0x3d372713, v80
	v_mul_f32_e32 v81, v81, v80
	v_fma_f32 v81, v81, v80, v80
	v_mul_f32_e32 v81, 0x3fcc422a, v81
	v_mul_f32_e32 v81, 0xbfb8aa3b, v81
	v_exp_f32_e32 v81, v81
	s_nop 0
	v_add_f32_e32 v81, 1.0, v81
	v_rcp_f32_e32 v81, v81
	s_nop 0
	v_mul_f32_e32 v81, v80, v81
	v_mul_f32_e32 v7, v7, v81
	v_add_f32_e32 v8, v8, v24
	v_lshlrev_b32_e32 v80, 16, v244
	v_mul_f32_e32 v81, 0x3d372713, v80
	v_mul_f32_e32 v81, v81, v80
	v_fma_f32 v81, v81, v80, v80
	v_mul_f32_e32 v81, 0x3fcc422a, v81
	v_mul_f32_e32 v81, 0xbfb8aa3b, v81
	v_exp_f32_e32 v81, v81
	s_nop 0
	v_add_f32_e32 v81, 1.0, v81
	v_rcp_f32_e32 v81, v81
	s_nop 0
	v_mul_f32_e32 v81, v80, v81
	v_mul_f32_e32 v8, v8, v81
	v_add_f32_e32 v9, v9, v25
	v_and_b32_e32 v80, 0xffff0000, v244
	v_mul_f32_e32 v81, 0x3d372713, v80
	v_mul_f32_e32 v81, v81, v80
	v_fma_f32 v81, v81, v80, v80
	v_mul_f32_e32 v81, 0x3fcc422a, v81
	v_mul_f32_e32 v81, 0xbfb8aa3b, v81
	v_exp_f32_e32 v81, v81
	s_nop 0
	v_add_f32_e32 v81, 1.0, v81
	v_rcp_f32_e32 v81, v81
	s_nop 0
	v_mul_f32_e32 v81, v80, v81
	v_mul_f32_e32 v9, v9, v81
	v_add_f32_e32 v10, v10, v26
	v_lshlrev_b32_e32 v80, 16, v245
	v_mul_f32_e32 v81, 0x3d372713, v80
	v_mul_f32_e32 v81, v81, v80
	v_fma_f32 v81, v81, v80, v80
	v_mul_f32_e32 v81, 0x3fcc422a, v81
	v_mul_f32_e32 v81, 0xbfb8aa3b, v81
	v_exp_f32_e32 v81, v81
	s_nop 0
	v_add_f32_e32 v81, 1.0, v81
	v_rcp_f32_e32 v81, v81
	s_nop 0
	v_mul_f32_e32 v81, v80, v81
	v_mul_f32_e32 v10, v10, v81
	v_add_f32_e32 v11, v11, v27
	v_and_b32_e32 v80, 0xffff0000, v245
	v_mul_f32_e32 v81, 0x3d372713, v80
	v_mul_f32_e32 v81, v81, v80
	v_fma_f32 v81, v81, v80, v80
	v_mul_f32_e32 v81, 0x3fcc422a, v81
	v_mul_f32_e32 v81, 0xbfb8aa3b, v81
	v_exp_f32_e32 v81, v81
	s_nop 0
	v_add_f32_e32 v81, 1.0, v81
	v_rcp_f32_e32 v81, v81
	s_nop 0
	v_mul_f32_e32 v81, v80, v81
	v_mul_f32_e32 v11, v11, v81
	v_add_f32_e32 v12, v12, v28
	v_lshlrev_b32_e32 v80, 16, v246
	v_mul_f32_e32 v81, 0x3d372713, v80
	v_mul_f32_e32 v81, v81, v80
	v_fma_f32 v81, v81, v80, v80
	v_mul_f32_e32 v81, 0x3fcc422a, v81
	v_mul_f32_e32 v81, 0xbfb8aa3b, v81
	v_exp_f32_e32 v81, v81
	s_nop 0
	v_add_f32_e32 v81, 1.0, v81
	v_rcp_f32_e32 v81, v81
	s_nop 0
	v_mul_f32_e32 v81, v80, v81
	v_mul_f32_e32 v12, v12, v81
	v_add_f32_e32 v13, v13, v29
	v_and_b32_e32 v80, 0xffff0000, v246
	v_mul_f32_e32 v81, 0x3d372713, v80
	v_mul_f32_e32 v81, v81, v80
	v_fma_f32 v81, v81, v80, v80
	v_mul_f32_e32 v81, 0x3fcc422a, v81
	v_mul_f32_e32 v81, 0xbfb8aa3b, v81
	v_exp_f32_e32 v81, v81
	s_nop 0
	v_add_f32_e32 v81, 1.0, v81
	v_rcp_f32_e32 v81, v81
	s_nop 0
	v_mul_f32_e32 v81, v80, v81
	v_mul_f32_e32 v13, v13, v81
	v_add_f32_e32 v14, v14, v30
	v_lshlrev_b32_e32 v80, 16, v247
	v_mul_f32_e32 v81, 0x3d372713, v80
	v_mul_f32_e32 v81, v81, v80
	v_fma_f32 v81, v81, v80, v80
	v_mul_f32_e32 v81, 0x3fcc422a, v81
	v_mul_f32_e32 v81, 0xbfb8aa3b, v81
	v_exp_f32_e32 v81, v81
	s_nop 0
	v_add_f32_e32 v81, 1.0, v81
	v_rcp_f32_e32 v81, v81
	s_nop 0
	v_mul_f32_e32 v81, v80, v81
	v_mul_f32_e32 v14, v14, v81
	v_add_f32_e32 v15, v15, v31
	v_and_b32_e32 v80, 0xffff0000, v247
	v_mul_f32_e32 v81, 0x3d372713, v80
	v_mul_f32_e32 v81, v81, v80
	v_fma_f32 v81, v81, v80, v80
	v_mul_f32_e32 v81, 0x3fcc422a, v81
	v_mul_f32_e32 v81, 0xbfb8aa3b, v81
	v_exp_f32_e32 v81, v81
	s_nop 0
	v_add_f32_e32 v81, 1.0, v81
	v_rcp_f32_e32 v81, v81
	s_nop 0
	v_mul_f32_e32 v81, v80, v81
	v_mul_f32_e32 v15, v15, v81
	v_cvt_pk_bf16_f32 v16, v0, v1
	v_cvt_pk_bf16_f32 v17, v2, v3
	v_cvt_pk_bf16_f32 v18, v4, v5
	v_cvt_pk_bf16_f32 v19, v6, v7
	v_cvt_pk_bf16_f32 v20, v8, v9
	v_cvt_pk_bf16_f32 v21, v10, v11
	v_cvt_pk_bf16_f32 v22, v12, v13
	v_cvt_pk_bf16_f32 v23, v14, v15
	global_store_dwordx4 v193, v[16:19], s[0:1]
	global_store_dwordx4 v193, v[20:23], s[0:1] offset:16
	s_waitcnt vmcnt(0) lgkmcnt(0)
	s_barrier
; template <int PASS>
; __device__ __forceinline__ void lru_tile_phase(const Params& p, int jl, int Mrows, char* smem, int tid, int bid) {
;     ...
;     __syncthreads();
;   }
; }
	s_add_u32 s6, s6, s71
	s_cmp_lt_u32 s6, 0x1100
	s_cbranch_scc1 .Llru2_job
	v_readlane_b32 s36, v255, 11
	v_readlane_b32 s37, v255, 12
	v_readlane_b32 s38, v255, 13
	v_readlane_b32 s39, v255, 14
	v_readlane_b32 s40, v255, 15
	v_readlane_b32 s41, v255, 16
	v_readlane_b32 s42, v255, 17
	v_readlane_b32 s43, v255, 18
	v_readlane_b32 s44, v255, 19
	v_readlane_b32 s45, v255, 20
	v_readlane_b32 s46, v255, 21
	v_readlane_b32 s47, v255, 22
	v_readlane_b32 s48, v255, 23
	v_readlane_b32 s49, v255, 24
	v_readlane_b32 s50, v255, 25
	v_readlane_b32 s51, v255, 26
